# dilated attention: score-independent mask/ALiBi-bias math hoisted into the QK^T MFMA gaps (32 spare VGPRs), one v_fma per score after QK^T
# speedup vs baseline: 1.0209x; 1.0209x over previous
; #define SBAR() __builtin_amdgcn_sched_barrier(0)
; #define KRD(f, d0, kb) asm volatile("ds_read_b128 %0, %2 offset:%3\n\tds_read_b128 %1, %2 offset:%4" : "=&v"(f.a), "=&v"(f.b) : "v"((kb) + koff[(d0) & 3]), "i"(((d0) >> 2) * 128), "i"(((d0) >> 2) * 128 + 8192) : "memory")
; #define QMM(f, d0) do { pA0 = __builtin_amdgcn_mfma_f32_32x32x16_bf16(f.a, qr[d0], pA0, 0, 0, 0); pA1 = __builtin_amdgcn_mfma_f32_32x32x16_bf16(f.b, qr[d0], pA1, 0, 0, 0); } while (0)
; #define LW(n) do { asm volatile("s_waitcnt lgkmcnt(" #n ")" ::: "memory"); SBAR(); } while (0)
; __device__ __forceinline__ void partialSM_dil(f32x16& p0, f32x16& p1, float& m_reg, float& mn, float& alpha, float dq, float dlo, float dhi, float nslopeC) {
;     ...
;   for (int r = 0; r < 16; ++r) {
;     const float d0 = dq + (float)crow0(r), d1 = d0 + 32.f;
;     const float t0 = fmaf(p0[r], C, nslopeC * fabsf(d0)), t1 = fmaf(p1[r], C, nslopeC * fabsf(d1));
;     p0[r] = (d0 >= dlo && d0 <= dhi) ? t0 : -1e30f;
;     p1[r] = (d1 >= dlo && d1 <= dhi) ? t1 : -1e30f;
;   }
;     ...
;       if (j >= rlo && j <= rlo + 2) {
;         SBAR();
;         { const int kb_ = kbase0 + (j & 3) * (int)SHM_K; KFrag k0_, k1_, k2_;
;           KRD(k0_, 0, kb_); KRD(k1_, 1, kb_); KRD(k2_, 2, kb_); pA0 = f32x16{}; pA1 = f32x16{};
;           LW(4); QMM(k0_, 0); SBAR(); KRD(k0_, 3, kb_);
;           LW(4); QMM(k1_, 1); SBAR(); KRD(k1_, 4, kb_);
;           LW(4); QMM(k2_, 2); SBAR(); KRD(k2_, 5, kb_);
;           LW(4); QMM(k0_, 3); SBAR(); KRD(k0_, 6, kb_);
;           LW(4); QMM(k1_, 4); SBAR(); KRD(k1_, 7, kb_);
;           LW(4); QMM(k2_, 5); SBAR();
;           LW(2); QMM(k0_, 6); SBAR();
;           LW(0); QMM(k1_, 7); SBAR(); }
.LBB0_142:
	s_cmp_lt_i32 s46, s23
	s_cselect_b64 s[0:1], -1, 0
	s_cmp_gt_i32 s46, s25
	s_cselect_b64 s[44:45], -1, 0
	s_or_b64 s[0:1], s[0:1], s[44:45]
	s_and_b64 vcc, exec, s[0:1]
	s_cbranch_vccnz .LBB0_148
	s_and_b32 s47, s21, 0xc000
	s_cmp_lg_u32 0, -1
	s_cselect_b32 s0, 0, 0
	s_add_i32 s0, s47, s0
	v_add_u32_e32 v0, s0, v145
	ds_read_b128 v[66:69], v0 offset:0
	ds_read_b128 v[70:73], v0 offset:0x2000
	v_add_u32_e32 v178, s0, v146
	ds_read_b128 v[154:157], v178 offset:0
	ds_read_b128 v[158:161], v178 offset:0x2000
	v_add_u32_e32 v179, s0, v148
	ds_read_b128 v[162:165], v179 offset:0
	ds_read_b128 v[166:169], v179 offset:0x2000
	s_waitcnt lgkmcnt(4)
	v_mfma_f32_32x32x16_bf16 v[82:97], v[66:69], v[122:125], 0
	v_mov_b32_e32 v236, v214
	s_movk_i32 s44, 0xffe0
	v_ashrrev_i32_e32 v232, 1, v236
	v_and_b32_e32 v231, 0xffffffe0, v232
	v_and_b32_e32 v230, 31, v236
	v_bfi_b32 v232, s44, v232, v236
	v_lshrrev_b32_e32 v236, 3, v236
	v_and_b32_e32 v236, 4, v236
	v_sub_u32_e32 v236, v236, v230
	v_add_u32_e32 v232, s40, v232
	v_sub_u32_e32 v236, v236, v231
	v_sub_u32_e32 v231, 0, v232
	v_xad_u32 v232, v232, -1, s11
	v_add_u32_e32 v236, s37, v236
	v_mfma_f32_32x32x16_bf16 v[66:81], v[70:73], v[122:125], 0
	v_cvt_f32_i32_e32 v231, v231
	v_cvt_f32_i32_e32 v232, v232
	v_cvt_f32_i32_e32 v230, v236
	v_max_f32_e32 v231, 0xc2800000, v231
	v_min_f32_e32 v232, 0x42800000, v232
	v_mov_b32_e32 v235, 0x3e0293ee
	v_add_f32_e32 v234, 0x42000000, v230
	v_mul_f32_e64 v181, v143, |v230|
	v_cmp_nle_f32_e32 vcc, v231, v230
	v_cmp_nge_f32_e64 s[44:45], v232, v230
	v_mul_f32_e64 v182, v143, |v234|
	s_or_b64 vcc, vcc, s[44:45]
	v_cndmask_b32_e32 v181, v181, v227, vcc
	v_cmp_nle_f32_e32 vcc, v231, v234
	v_add_u32_e32 v180, s0, v149
	ds_read_b128 v[170:173], v180 offset:0
	ds_read_b128 v[174:177], v180 offset:0x2000
	s_waitcnt lgkmcnt(4)
	v_mfma_f32_32x32x16_bf16 v[82:97], v[154:157], v[98:101], v[82:97]
	v_cmp_nge_f32_e64 s[44:45], v232, v234
	s_nop 0
	s_or_b64 vcc, vcc, s[44:45]
	v_cndmask_b32_e32 v182, v182, v227, vcc
	v_add_f32_e32 v233, 0x3f800000, v230
	v_add_f32_e32 v234, 0x42000000, v233
	v_mul_f32_e64 v183, v143, |v233|
	v_cmp_nle_f32_e32 vcc, v231, v233
	v_cmp_nge_f32_e64 s[44:45], v232, v233
	v_mul_f32_e64 v184, v143, |v234|
	s_or_b64 vcc, vcc, s[44:45]
	v_cndmask_b32_e32 v183, v183, v227, vcc
	v_cmp_nle_f32_e32 vcc, v231, v234
	v_cmp_nge_f32_e64 s[44:45], v232, v234
	v_mfma_f32_32x32x16_bf16 v[66:81], v[158:161], v[98:101], v[66:81]
	s_nop 0
	s_or_b64 vcc, vcc, s[44:45]
	v_cndmask_b32_e32 v184, v184, v227, vcc
	v_add_f32_e32 v233, 0x40000000, v230
	v_add_f32_e32 v234, 0x42000000, v233
	v_mul_f32_e64 v185, v143, |v233|
	v_cmp_nle_f32_e32 vcc, v231, v233
	v_cmp_nge_f32_e64 s[44:45], v232, v233
	v_mul_f32_e64 v186, v143, |v234|
	s_or_b64 vcc, vcc, s[44:45]
	v_cndmask_b32_e32 v185, v185, v227, vcc
	v_cmp_nle_f32_e32 vcc, v231, v234
	v_cmp_nge_f32_e64 s[44:45], v232, v234
	s_nop 0
	ds_read_b128 v[154:157], v0 offset:0x80
	ds_read_b128 v[158:161], v0 offset:0x2080
	s_waitcnt lgkmcnt(4)
	v_mfma_f32_32x32x16_bf16 v[82:97], v[162:165], v[102:105], v[82:97]
	s_or_b64 vcc, vcc, s[44:45]
	v_cndmask_b32_e32 v186, v186, v227, vcc
	v_add_f32_e32 v233, 0x40400000, v230
	v_add_f32_e32 v234, 0x42000000, v233
	v_mul_f32_e64 v187, v143, |v233|
	v_cmp_nle_f32_e32 vcc, v231, v233
	v_cmp_nge_f32_e64 s[44:45], v232, v233
	v_mul_f32_e64 v188, v143, |v234|
	s_or_b64 vcc, vcc, s[44:45]
	v_cndmask_b32_e32 v187, v187, v227, vcc
	v_cmp_nle_f32_e32 vcc, v231, v234
	v_cmp_nge_f32_e64 s[44:45], v232, v234
	s_nop 0
	s_or_b64 vcc, vcc, s[44:45]
	v_mfma_f32_32x32x16_bf16 v[66:81], v[166:169], v[102:105], v[66:81]
	v_cndmask_b32_e32 v188, v188, v227, vcc
	v_add_f32_e32 v233, 0x41000000, v230
	v_add_f32_e32 v234, 0x42000000, v233
	v_mul_f32_e64 v189, v143, |v233|
	v_cmp_nle_f32_e32 vcc, v231, v233
	v_cmp_nge_f32_e64 s[44:45], v232, v233
	v_mul_f32_e64 v190, v143, |v234|
	s_or_b64 vcc, vcc, s[44:45]
	v_cndmask_b32_e32 v189, v189, v227, vcc
	v_cmp_nle_f32_e32 vcc, v231, v234
	v_cmp_nge_f32_e64 s[44:45], v232, v234
	s_nop 0
	s_or_b64 vcc, vcc, s[44:45]
	v_cndmask_b32_e32 v190, v190, v227, vcc
	ds_read_b128 v[162:165], v178 offset:0x80
	ds_read_b128 v[166:169], v178 offset:0x2080
	s_waitcnt lgkmcnt(4)
	v_mfma_f32_32x32x16_bf16 v[82:97], v[170:173], v[106:109], v[82:97]
	v_add_f32_e32 v233, 0x41100000, v230
	v_add_f32_e32 v234, 0x42000000, v233
	v_mul_f32_e64 v191, v143, |v233|
	v_cmp_nle_f32_e32 vcc, v231, v233
	v_cmp_nge_f32_e64 s[44:45], v232, v233
	v_mul_f32_e64 v192, v143, |v234|
	s_or_b64 vcc, vcc, s[44:45]
	v_cndmask_b32_e32 v191, v191, v227, vcc
	v_cmp_nle_f32_e32 vcc, v231, v234
	v_cmp_nge_f32_e64 s[44:45], v232, v234
	s_nop 0
	s_or_b64 vcc, vcc, s[44:45]
	v_cndmask_b32_e32 v192, v192, v227, vcc
	v_add_f32_e32 v233, 0x41200000, v230
	v_mfma_f32_32x32x16_bf16 v[66:81], v[174:177], v[106:109], v[66:81]
	v_add_f32_e32 v234, 0x42000000, v233
	v_mul_f32_e64 v193, v143, |v233|
	v_cmp_nle_f32_e32 vcc, v231, v233
	v_cmp_nge_f32_e64 s[44:45], v232, v233
	v_mul_f32_e64 v194, v143, |v234|
	s_or_b64 vcc, vcc, s[44:45]
	v_cndmask_b32_e32 v193, v193, v227, vcc
	v_cmp_nle_f32_e32 vcc, v231, v234
	v_cmp_nge_f32_e64 s[44:45], v232, v234
	s_nop 0
	s_or_b64 vcc, vcc, s[44:45]
	v_cndmask_b32_e32 v194, v194, v227, vcc
	v_add_f32_e32 v233, 0x41300000, v230
	v_add_f32_e32 v234, 0x42000000, v233
	ds_read_b128 v[170:173], v179 offset:0x80
	ds_read_b128 v[174:177], v179 offset:0x2080
	s_waitcnt lgkmcnt(4)
; #define SBAR() __builtin_amdgcn_sched_barrier(0)
; #define RESC(a) do { if (__any((a) < 1.f)) { if (hi == 0) al_l[r32] = (a); asm volatile("s_waitcnt lgkmcnt(0)" ::: "memory"); \
;     for (int d = 0; d < 4; ++d) for (int r = 0; r < 16; ++r) o[d][r] *= al_l[crow(r, hi)]; } } while (0)
; #define PSM(P0, P1, MN, AL, jt) do { if constexpr (DIL) { const int t_ = otid(), iq_ = (t_ >> 6) * QBLK + (t_ & 31), hi_ = (t_ >> 5) & 1; \
;       partialSM_dil(P0, P1, m_reg, MN, AL, (float)(-64 - iq_ + 4 * hi_ + 64 * (jt)), fmaxf(-64.f, (float)(-(i0 + iq_))), fminf(64.f, (float)(nsub - 1 - (i0 + iq_))), nslopeC); } \
;     else partialSM(P0, P1, m_reg, MN, AL); } while (0)
; #define KRD(f, d0, kb) asm volatile("ds_read_b128 %0, %2 offset:%3\n\tds_read_b128 %1, %2 offset:%4" : "=&v"(f.a), "=&v"(f.b) : "v"((kb) + koff[(d0) & 3]), "i"(((d0) >> 2) * 128), "i"(((d0) >> 2) * 128 + 8192) : "memory")
; #define QMM(f, d0) do { pA0 = __builtin_amdgcn_mfma_f32_32x32x16_bf16(f.a, qr[d0], pA0, 0, 0, 0); pA1 = __builtin_amdgcn_mfma_f32_32x32x16_bf16(f.b, qr[d0], pA1, 0, 0, 0); } while (0)
; __device__ __forceinline__ void partialSM_dil(f32x16& p0, f32x16& p1, float& m_reg, float& mn, float& alpha, float dq, float dlo, float dhi, float nslopeC) {
;     ...
;   for (int r = 0; r < 16; ++r) {
;     const float d0 = dq + (float)crow0(r), d1 = d0 + 32.f;
;     const float t0 = fmaf(p0[r], C, nslopeC * fabsf(d0)), t1 = fmaf(p1[r], C, nslopeC * fabsf(d1));
;     p0[r] = (d0 >= dlo && d0 <= dhi) ? t0 : -1e30f;
;     p1[r] = (d1 >= dlo && d1 <= dhi) ? t1 : -1e30f;
;   }
;   float pmax = p0[0];
; #pragma unroll
;   for (int r = 1; r < 16; ++r) pmax = fmaxf(pmax, p0[r]);
; #pragma unroll
;   for (int r = 0; r < 16; ++r) pmax = fmaxf(pmax, p1[r]);
;   { auto rr = __builtin_amdgcn_permlane32_swap(__float_as_uint(pmax), __float_as_uint(pmax), false, false);
;     pmax = fmaxf(__uint_as_float(rr[0]), __uint_as_float(rr[1])); }
;   if (__builtin_expect(__all(pmax - m_reg <= THR * LOG2E), 1)) { mn = m_reg; alpha = 1.f; }
;   else { mn = fmaxf(m_reg, pmax); alpha = __builtin_amdgcn_exp2f(m_reg - mn); m_reg = mn; }
;     ...
;           LW(4); QMM(k0_, 3); SBAR(); KRD(k0_, 6, kb_);
;           LW(4); QMM(k1_, 4); SBAR(); KRD(k1_, 7, kb_);
;           LW(4); QMM(k2_, 5); SBAR();
;           LW(2); QMM(k0_, 6); SBAR();
;           LW(0); QMM(k1_, 7); SBAR(); }
;         PSM(pA0, pA1, mnA, alA, j); RESC(alA);
	v_mfma_f32_32x32x16_bf16 v[82:97], v[154:157], v[110:113], v[82:97]
	v_mul_f32_e64 v195, v143, |v233|
	v_cmp_nle_f32_e32 vcc, v231, v233
	v_cmp_nge_f32_e64 s[44:45], v232, v233
	v_mul_f32_e64 v196, v143, |v234|
	s_or_b64 vcc, vcc, s[44:45]
	v_cndmask_b32_e32 v195, v195, v227, vcc
	v_cmp_nle_f32_e32 vcc, v231, v234
	v_cmp_nge_f32_e64 s[44:45], v232, v234
	s_nop 0
	s_or_b64 vcc, vcc, s[44:45]
	v_cndmask_b32_e32 v196, v196, v227, vcc
	v_add_f32_e32 v233, 0x41800000, v230
	v_add_f32_e32 v234, 0x42000000, v233
	v_mul_f32_e64 v197, v143, |v233|
	v_mfma_f32_32x32x16_bf16 v[66:81], v[158:161], v[110:113], v[66:81]
	v_cmp_nle_f32_e32 vcc, v231, v233
	v_cmp_nge_f32_e64 s[44:45], v232, v233
	v_mul_f32_e64 v198, v143, |v234|
	s_or_b64 vcc, vcc, s[44:45]
	v_cndmask_b32_e32 v197, v197, v227, vcc
	v_cmp_nle_f32_e32 vcc, v231, v234
	v_cmp_nge_f32_e64 s[44:45], v232, v234
	s_nop 0
	s_or_b64 vcc, vcc, s[44:45]
	v_cndmask_b32_e32 v198, v198, v227, vcc
	v_add_f32_e32 v233, 0x41880000, v230
	v_add_f32_e32 v234, 0x42000000, v233
	v_mul_f32_e64 v199, v143, |v233|
	v_cmp_nle_f32_e32 vcc, v231, v233
	ds_read_b128 v[154:157], v180 offset:0x80
	ds_read_b128 v[158:161], v180 offset:0x2080
	s_waitcnt lgkmcnt(4)
	v_mfma_f32_32x32x16_bf16 v[82:97], v[162:165], v[114:117], v[82:97]
	v_cmp_nge_f32_e64 s[44:45], v232, v233
	v_mul_f32_e64 v200, v143, |v234|
	s_or_b64 vcc, vcc, s[44:45]
	v_cndmask_b32_e32 v199, v199, v227, vcc
	v_cmp_nle_f32_e32 vcc, v231, v234
	v_cmp_nge_f32_e64 s[44:45], v232, v234
	s_nop 0
	s_or_b64 vcc, vcc, s[44:45]
	v_cndmask_b32_e32 v200, v200, v227, vcc
	v_add_f32_e32 v233, 0x41900000, v230
	v_add_f32_e32 v234, 0x42000000, v233
	v_mul_f32_e64 v201, v143, |v233|
	v_cmp_nle_f32_e32 vcc, v231, v233
	v_cmp_nge_f32_e64 s[44:45], v232, v233
	v_mfma_f32_32x32x16_bf16 v[66:81], v[166:169], v[114:117], v[66:81]
	v_mul_f32_e64 v202, v143, |v234|
	s_or_b64 vcc, vcc, s[44:45]
	v_cndmask_b32_e32 v201, v201, v227, vcc
	v_cmp_nle_f32_e32 vcc, v231, v234
	v_cmp_nge_f32_e64 s[44:45], v232, v234
	s_nop 0
	s_or_b64 vcc, vcc, s[44:45]
	v_cndmask_b32_e32 v202, v202, v227, vcc
	v_add_f32_e32 v233, 0x41980000, v230
	v_add_f32_e32 v234, 0x42000000, v233
	v_mul_f32_e64 v203, v143, |v233|
	v_cmp_nle_f32_e32 vcc, v231, v233
	v_cmp_nge_f32_e64 s[44:45], v232, v233
	v_mul_f32_e64 v204, v143, |v234|
	s_waitcnt lgkmcnt(2)
	v_mfma_f32_32x32x16_bf16 v[82:97], v[170:173], v[118:121], v[82:97]
	s_or_b64 vcc, vcc, s[44:45]
	v_cndmask_b32_e32 v203, v203, v227, vcc
	v_cmp_nle_f32_e32 vcc, v231, v234
	v_cmp_nge_f32_e64 s[44:45], v232, v234
	s_nop 0
	s_or_b64 vcc, vcc, s[44:45]
	v_cndmask_b32_e32 v204, v204, v227, vcc
	v_add_f32_e32 v233, 0x41c00000, v230
	v_add_f32_e32 v234, 0x42000000, v233
	v_mul_f32_e64 v205, v143, |v233|
	v_cmp_nle_f32_e32 vcc, v231, v233
	v_cmp_nge_f32_e64 s[44:45], v232, v233
	v_mul_f32_e64 v206, v143, |v234|
	s_or_b64 vcc, vcc, s[44:45]
	v_mfma_f32_32x32x16_bf16 v[66:81], v[174:177], v[118:121], v[66:81]
	v_cndmask_b32_e32 v205, v205, v227, vcc
	v_cmp_nle_f32_e32 vcc, v231, v234
	v_cmp_nge_f32_e64 s[44:45], v232, v234
	s_nop 0
	s_or_b64 vcc, vcc, s[44:45]
	v_cndmask_b32_e32 v206, v206, v227, vcc
	v_add_f32_e32 v233, 0x41c80000, v230
	v_add_f32_e32 v234, 0x42000000, v233
	v_mul_f32_e64 v208, v143, |v233|
	v_cmp_nle_f32_e32 vcc, v231, v233
	v_cmp_nge_f32_e64 s[44:45], v232, v233
	v_mul_f32_e64 v209, v143, |v234|
	s_or_b64 vcc, vcc, s[44:45]
	v_cndmask_b32_e32 v208, v208, v227, vcc
	s_waitcnt lgkmcnt(0)
	v_mfma_f32_32x32x16_bf16 v[82:97], v[154:157], v[126:129], v[82:97]
	v_cmp_nle_f32_e32 vcc, v231, v234
	v_cmp_nge_f32_e64 s[44:45], v232, v234
	s_nop 0
	s_or_b64 vcc, vcc, s[44:45]
	v_cndmask_b32_e32 v209, v209, v227, vcc
	v_add_f32_e32 v233, 0x41d00000, v230
	v_add_f32_e32 v234, 0x42000000, v233
	v_mul_f32_e64 v210, v143, |v233|
	v_cmp_nle_f32_e32 vcc, v231, v233
	v_cmp_nge_f32_e64 s[44:45], v232, v233
	v_mul_f32_e64 v211, v143, |v234|
	s_or_b64 vcc, vcc, s[44:45]
	v_cndmask_b32_e32 v210, v210, v227, vcc
	v_cmp_nle_f32_e32 vcc, v231, v234
	v_mfma_f32_32x32x16_bf16 v[66:81], v[158:161], v[126:129], v[66:81]
	v_cmp_nge_f32_e64 s[44:45], v232, v234
	s_nop 0
	s_or_b64 vcc, vcc, s[44:45]
	v_cndmask_b32_e32 v211, v211, v227, vcc
	v_add_f32_e32 v233, 0x41d80000, v230
	v_add_f32_e32 v234, 0x42000000, v233
	v_mul_f32_e64 v212, v143, |v233|
	v_cmp_nle_f32_e32 vcc, v231, v233
	v_cmp_nge_f32_e64 s[44:45], v232, v233
	v_mul_f32_e64 v213, v143, |v234|
	s_or_b64 vcc, vcc, s[44:45]
	v_cndmask_b32_e32 v212, v212, v227, vcc
	v_cmp_nle_f32_e32 vcc, v231, v234
	v_cmp_nge_f32_e64 s[44:45], v232, v234
	s_nop 0
	s_or_b64 vcc, vcc, s[44:45]
	v_cndmask_b32_e32 v213, v213, v227, vcc
	v_fma_f32 v0, v82, v235, v181
	v_fma_f32 v66, v66, v235, v182
	v_fma_f32 v82, v67, v235, v184
	v_fma_f32 v67, v83, v235, v183
	v_fma_f32 v83, v68, v235, v186
	v_fma_f32 v68, v84, v235, v185
	v_fma_f32 v84, v69, v235, v188
	v_fma_f32 v69, v85, v235, v187
	v_fma_f32 v85, v70, v235, v190
	v_fma_f32 v70, v86, v235, v189
	v_fma_f32 v86, v71, v235, v192
	v_fma_f32 v71, v87, v235, v191
	v_fma_f32 v87, v72, v235, v194
	v_fma_f32 v72, v88, v235, v193
	v_fma_f32 v88, v73, v235, v196
	v_fma_f32 v73, v89, v235, v195
	v_fma_f32 v89, v74, v235, v198
	v_fma_f32 v74, v90, v235, v197
	v_fma_f32 v90, v75, v235, v200
	v_fma_f32 v75, v91, v235, v199
	v_fma_f32 v91, v76, v235, v202
	v_fma_f32 v76, v92, v235, v201
	v_fma_f32 v92, v77, v235, v204
	v_fma_f32 v77, v93, v235, v203
	v_fma_f32 v93, v78, v235, v206
	v_fma_f32 v78, v94, v235, v205
	v_fma_f32 v94, v95, v235, v208
	v_fma_f32 v95, v79, v235, v209
	v_fma_f32 v237, v96, v235, v210
	v_fma_f32 v96, v80, v235, v211
	v_fma_f32 v238, v97, v235, v212
	v_fma_f32 v97, v81, v235, v213
	v_mov_b32_e32 v80, v237
	v_mov_b32_e32 v81, v238
	v_max_f32_e32 v79, v0, v67
	v_max3_f32 v79, v79, v68, v69
	v_max3_f32 v79, v79, v70, v71
	v_max3_f32 v79, v79, v72, v73
	v_max3_f32 v79, v79, v74, v75
	v_max3_f32 v79, v79, v76, v77
	v_max3_f32 v79, v79, v78, v94
	v_max3_f32 v79, v79, v80, v81
	v_max3_f32 v79, v79, v66, v82
	v_max3_f32 v79, v79, v83, v84
	v_max3_f32 v79, v79, v85, v86
	v_max3_f32 v79, v79, v87, v88
	v_max3_f32 v79, v79, v89, v90
	v_max3_f32 v79, v79, v91, v92
	v_max3_f32 v79, v79, v93, v95
	v_max3_f32 v79, v79, v96, v97
	v_mov_b32_e32 v154, v79
	s_nop 1
	v_permlane32_swap_b32_e32 v79, v154
	v_max_f32_e32 v154, v154, v154
	v_max_f32_e32 v79, v79, v79
	v_max_f32_e32 v79, v79, v154
	v_max_f32_e32 v154, v144, v144
	v_max_f32_e32 v154, v154, v79
	v_sub_f32_e32 v155, v79, v144
	v_sub_f32_e32 v79, v144, v154
	v_exp_f32_e32 v79, v79
	s_mov_b32 s0, 0x4138aa3b
	v_cmp_ge_f32_e32 vcc, s0, v155
	s_cmp_eq_u64 vcc, exec
	s_cselect_b64 s[0:1], -1, 0
	v_cndmask_b32_e64 v79, v79, 1.0, s[0:1]
	v_cmp_gt_f32_e32 vcc, 1.0, v79
	s_cbranch_vccz .LBB0_147
	s_and_saveexec_b64 s[44:45], s[38:39]
	ds_write_b32 v147, v79 offset:128
	s_or_b64 exec, exec, s[44:45]
	s_waitcnt lgkmcnt(0)
	v_add_u32_e32 v155, s15, v130
	ds_read_b128 v[156:159], v155 offset:224
	ds_read_b128 v[160:163], v155 offset:192
	ds_read_b128 v[164:167], v155 offset:160
	ds_read_b128 v[168:171], v155 offset:128
	s_waitcnt lgkmcnt(0)
	v_pk_mul_f32 v[62:63], v[62:63], v[156:157]
	v_pk_mul_f32 v[58:59], v[58:59], v[160:161]
	v_pk_mul_f32 v[54:55], v[54:55], v[164:165]
	v_pk_mul_f32 v[64:65], v[64:65], v[158:159]
	v_pk_mul_f32 v[60:61], v[60:61], v[162:163]
	v_pk_mul_f32 v[56:57], v[56:57], v[166:167]
	v_pk_mul_f32 v[52:53], v[52:53], v[170:171]
	v_pk_mul_f32 v[50:51], v[50:51], v[168:169]
	v_pk_mul_f32 v[46:47], v[46:47], v[156:157]
	v_pk_mul_f32 v[42:43], v[42:43], v[160:161]
	v_pk_mul_f32 v[38:39], v[38:39], v[164:165]
	v_pk_mul_f32 v[48:49], v[48:49], v[158:159]
	v_pk_mul_f32 v[44:45], v[44:45], v[162:163]
	v_pk_mul_f32 v[40:41], v[40:41], v[166:167]
	v_pk_mul_f32 v[36:37], v[36:37], v[170:171]
	v_pk_mul_f32 v[34:35], v[34:35], v[168:169]
	v_pk_mul_f32 v[30:31], v[30:31], v[156:157]
	v_pk_mul_f32 v[26:27], v[26:27], v[160:161]
	v_pk_mul_f32 v[22:23], v[22:23], v[164:165]
	v_pk_mul_f32 v[32:33], v[32:33], v[158:159]
	v_pk_mul_f32 v[28:29], v[28:29], v[162:163]
	v_pk_mul_f32 v[24:25], v[24:25], v[166:167]
	v_pk_mul_f32 v[20:21], v[20:21], v[170:171]
	v_pk_mul_f32 v[18:19], v[18:19], v[168:169]
	v_pk_mul_f32 v[14:15], v[14:15], v[156:157]
	v_pk_mul_f32 v[10:11], v[10:11], v[160:161]
	v_pk_mul_f32 v[6:7], v[6:7], v[164:165]
	v_pk_mul_f32 v[16:17], v[16:17], v[158:159]
	v_pk_mul_f32 v[12:13], v[12:13], v[162:163]
	v_pk_mul_f32 v[8:9], v[8:9], v[166:167]
	v_pk_mul_f32 v[4:5], v[4:5], v[170:171]
	v_pk_mul_f32 v[2:3], v[2:3], v[168:169]
